# v20 + attention epilogue: 8 subln gain loads hoisted above the O stores
# baseline (speedup 1.0000x reference)
.LBB0_133:
	global_load_dwordx4 v[222:225], v[136:137], off
	global_load_dwordx4 v[226:229], v[136:137], off offset:64
	global_load_dwordx4 v[230:233], v[136:137], off offset:128
	global_load_dwordx4 v[234:237], v[136:137], off offset:192
	global_load_dwordx4 v[238:241], v[136:137], off offset:256
	global_load_dwordx4 v[242:245], v[136:137], off offset:320
	global_load_dwordx4 v[246:249], v[136:137], off offset:384
	global_load_dwordx4 v[172:175], v[136:137], off offset:448
	v_div_scale_f32 v0, s[6:7], v128, v128, 1.0
	v_rcp_f32_e32 v2, v0
	v_mov_b32_e32 v163, v1
	v_fma_f32 v3, -v0, v2, 1.0
	v_fmac_f32_e32 v2, v3, v2
	v_div_scale_f32 v3, vcc, 1.0, v128, 1.0
	v_mul_f32_e32 v4, v3, v2
	v_fma_f32 v5, -v0, v4, v3
	v_fmac_f32_e32 v4, v5, v2
	v_fma_f32 v0, -v0, v4, v3
	v_div_fmas_f32 v0, v0, v2, v4
	v_div_scale_f32 v2, s[6:7], v116, v116, v190
	v_rcp_f32_e32 v3, v2
	v_div_fixup_f32 v0, v0, v128, 1.0
	v_fma_f32 v4, -v2, v3, 1.0
	v_fmac_f32_e32 v3, v4, v3
	v_div_scale_f32 v4, vcc, v190, v116, v190
	v_mul_f32_e32 v5, v4, v3
	v_fma_f32 v6, -v2, v5, v4
	v_fmac_f32_e32 v5, v6, v3
	v_fma_f32 v2, -v2, v5, v4
	v_div_fmas_f32 v2, v2, v3, v5
	v_div_fixup_f32 v2, v2, v116, v190
	v_pk_mul_f32 v[4:5], v[112:113], v[2:3] op_sel_hi:[1,0]
	v_pk_mul_f32 v[6:7], v[114:115], v[2:3] op_sel_hi:[1,0]
	v_pk_fma_f32 v[16:17], v[104:105], v[0:1], v[4:5] op_sel_hi:[1,0,1] neg_lo:[0,0,1] neg_hi:[0,0,1]
	v_pk_mul_f32 v[4:5], v[108:109], v[2:3] op_sel_hi:[1,0]
	v_pk_fma_f32 v[12:13], v[106:107], v[0:1], v[6:7] op_sel_hi:[1,0,1] neg_lo:[0,0,1] neg_hi:[0,0,1]
	v_pk_fma_f32 v[8:9], v[100:101], v[0:1], v[4:5] op_sel_hi:[1,0,1] neg_lo:[0,0,1] neg_hi:[0,0,1]
	v_pk_mul_f32 v[6:7], v[110:111], v[2:3] op_sel_hi:[1,0]
	v_mov_b32_e32 v10, v17
	v_mov_b32_e32 v11, v9
	v_pk_fma_f32 v[6:7], v[102:103], v[0:1], v[6:7] op_sel_hi:[1,0,1] neg_lo:[0,0,1] neg_hi:[0,0,1]
	v_mov_b32_e32 v4, v16
	v_mov_b32_e32 v5, v8
	v_pk_mul_f32 v[10:11], v[10:11], v[10:11]
	v_pk_mul_f32 v[14:15], v[98:99], v[2:3] op_sel_hi:[1,0]
	v_pk_fma_f32 v[4:5], v[4:5], v[4:5], v[10:11]
	v_mov_b32_e32 v10, v12
	v_mov_b32_e32 v11, v6
	v_pk_fma_f32 v[4:5], v[10:11], v[10:11], v[4:5]
	v_mov_b32_e32 v10, v13
	v_mov_b32_e32 v11, v7
	v_pk_fma_f32 v[4:5], v[10:11], v[10:11], v[4:5]
	v_pk_mul_f32 v[10:11], v[96:97], v[2:3] op_sel_hi:[1,0]
	s_waitcnt vmcnt(9)
	v_pk_fma_f32 v[28:29], v[90:91], v[0:1], v[14:15] op_sel_hi:[1,0,1] neg_lo:[0,0,1] neg_hi:[0,0,1]
	v_pk_fma_f32 v[32:33], v[88:89], v[0:1], v[10:11] op_sel_hi:[1,0,1] neg_lo:[0,0,1] neg_hi:[0,0,1]
	v_pk_mul_f32 v[10:11], v[92:93], v[2:3] op_sel_hi:[1,0]
	v_pk_mul_f32 v[14:15], v[94:95], v[2:3] op_sel_hi:[1,0]
	v_pk_fma_f32 v[24:25], v[84:85], v[0:1], v[10:11] op_sel_hi:[1,0,1] neg_lo:[0,0,1] neg_hi:[0,0,1]
	v_pk_fma_f32 v[20:21], v[86:87], v[0:1], v[14:15] op_sel_hi:[1,0,1] neg_lo:[0,0,1] neg_hi:[0,0,1]
	v_mov_b32_e32 v14, v25
	v_mov_b32_e32 v15, v33
	v_mov_b32_e32 v10, v24
	v_mov_b32_e32 v11, v32
	v_pk_mul_f32 v[14:15], v[14:15], v[14:15]
	s_nop 0
	v_pk_fma_f32 v[10:11], v[10:11], v[10:11], v[14:15]
	v_mov_b32_e32 v14, v20
	v_mov_b32_e32 v15, v28
	v_pk_fma_f32 v[10:11], v[14:15], v[14:15], v[10:11]
	v_mov_b32_e32 v14, v21
	v_mov_b32_e32 v15, v29
	v_pk_fma_f32 v[38:39], v[14:15], v[14:15], v[10:11]
	v_pk_mul_f32 v[10:11], v[80:81], v[2:3] op_sel_hi:[1,0]
	v_pk_mul_f32 v[14:15], v[82:83], v[2:3] op_sel_hi:[1,0]
	v_pk_fma_f32 v[36:37], v[72:73], v[0:1], v[10:11] op_sel_hi:[1,0,1] neg_lo:[0,0,1] neg_hi:[0,0,1]
	v_pk_mul_f32 v[10:11], v[76:77], v[2:3] op_sel_hi:[1,0]
	v_pk_fma_f32 v[34:35], v[74:75], v[0:1], v[14:15] op_sel_hi:[1,0,1] neg_lo:[0,0,1] neg_hi:[0,0,1]
	v_pk_mul_f32 v[14:15], v[78:79], v[2:3] op_sel_hi:[1,0]
	v_pk_fma_f32 v[22:23], v[68:69], v[0:1], v[10:11] op_sel_hi:[1,0,1] neg_lo:[0,0,1] neg_hi:[0,0,1]
	v_pk_fma_f32 v[18:19], v[70:71], v[0:1], v[14:15] op_sel_hi:[1,0,1] neg_lo:[0,0,1] neg_hi:[0,0,1]
	v_mov_b32_e32 v14, v23
	v_mov_b32_e32 v15, v37
	v_mov_b32_e32 v10, v22
	v_mov_b32_e32 v11, v36
	v_pk_mul_f32 v[14:15], v[14:15], v[14:15]
	s_nop 0
	v_pk_fma_f32 v[10:11], v[10:11], v[10:11], v[14:15]
	v_mov_b32_e32 v14, v18
	v_mov_b32_e32 v15, v34
	v_pk_fma_f32 v[10:11], v[14:15], v[14:15], v[10:11]
	v_mov_b32_e32 v14, v19
	v_mov_b32_e32 v15, v35
	s_waitcnt vmcnt(8)
	v_pk_fma_f32 v[40:41], v[14:15], v[14:15], v[10:11]
	v_pk_mul_f32 v[14:15], v[66:67], v[2:3] op_sel_hi:[1,0]
	v_pk_mul_f32 v[10:11], v[64:65], v[2:3] op_sel_hi:[1,0]
	v_pk_fma_f32 v[26:27], v[58:59], v[0:1], v[14:15] op_sel_hi:[1,0,1] neg_lo:[0,0,1] neg_hi:[0,0,1]
	v_pk_mul_f32 v[14:15], v[60:61], v[2:3] op_sel_hi:[1,0]
	v_pk_fma_f32 v[30:31], v[56:57], v[0:1], v[10:11] op_sel_hi:[1,0,1] neg_lo:[0,0,1] neg_hi:[0,0,1]
	v_pk_mul_f32 v[2:3], v[62:63], v[2:3] op_sel_hi:[1,0]
	v_pk_fma_f32 v[14:15], v[52:53], v[0:1], v[14:15] op_sel_hi:[1,0,1] neg_lo:[0,0,1] neg_hi:[0,0,1]
	v_pk_fma_f32 v[10:11], v[54:55], v[0:1], v[2:3] op_sel_hi:[1,0,1] neg_lo:[0,0,1] neg_hi:[0,0,1]
	v_mov_b32_e32 v42, v15
	v_mov_b32_e32 v43, v31
	v_add_f32_e32 v0, v4, v5
	v_mov_b32_e32 v2, v14
	v_mov_b32_e32 v3, v30
	v_pk_mul_f32 v[42:43], v[42:43], v[42:43]
	v_add_f32_e32 v0, v39, v0
	v_pk_fma_f32 v[2:3], v[2:3], v[2:3], v[42:43]
	v_mov_b32_e32 v42, v10
	v_mov_b32_e32 v43, v26
	v_add_f32_e32 v0, v38, v0
	v_pk_fma_f32 v[2:3], v[42:43], v[42:43], v[2:3]
	v_mov_b32_e32 v42, v11
	v_mov_b32_e32 v43, v27
	v_add_f32_e32 v0, v41, v0
	v_pk_fma_f32 v[2:3], v[42:43], v[42:43], v[2:3]
	v_add_f32_e32 v0, v40, v0
	v_add_f32_e32 v0, v3, v0
	v_add_f32_e32 v0, v2, v0
	ds_bpermute_b32 v2, v195, v0
	v_lshl_add_u64 v[38:39], v[164:165], 0, v[162:163]
	s_waitcnt lgkmcnt(0)
	v_add_f32_e32 v0, v0, v2
	ds_bpermute_b32 v2, v196, v0
	s_waitcnt lgkmcnt(0)
	v_add_f32_e32 v0, v0, v2
	v_fmamk_f32 v0, v0, 0x3c000000, v177
	v_cmp_gt_f32_e32 vcc, s34, v0
	v_mul_f32_e32 v2, 0x4b800000, v0
	s_nop 0
	v_cndmask_b32_e32 v0, v0, v2, vcc
	v_rsq_f32_e32 v0, v0
	s_nop 0
	v_mul_f32_e32 v2, 0x45800000, v0
	v_cndmask_b32_e32 v0, v0, v2, vcc
	v_mul_f32_e32 v0, v191, v0
	v_pk_mul_f32 v[16:17], v[16:17], v[0:1] op_sel_hi:[1,0]
	v_pk_mul_f32 v[12:13], v[12:13], v[0:1] op_sel_hi:[1,0]
	v_pk_mul_f32 v[8:9], v[8:9], v[0:1] op_sel_hi:[1,0]
	v_pk_mul_f32 v[6:7], v[6:7], v[0:1] op_sel_hi:[1,0]
	s_waitcnt vmcnt(0)
	s_nop 1
	v_mov_b32_e32 v2, v222
	v_mov_b32_e32 v3, v223
	v_mov_b32_e32 v4, v224
	v_mov_b32_e32 v5, v225
	v_pk_mul_f32 v[4:5], v[4:5], v[12:13]
	v_pk_mul_f32 v[2:3], v[2:3], v[16:17]
	s_nop 0
	v_cvt_pk_bf16_f32 v2, v2, v3
	v_cvt_pk_bf16_f32 v3, v4, v5
	global_store_dwordx2 v[38:39], v[2:3], off
	s_nop 1
	v_mov_b32_e32 v2, v226
	v_mov_b32_e32 v3, v227
	v_mov_b32_e32 v4, v228
	v_mov_b32_e32 v5, v229
	v_pk_mul_f32 v[4:5], v[4:5], v[6:7]
	v_pk_mul_f32 v[2:3], v[2:3], v[8:9]
	v_pk_mul_f32 v[6:7], v[32:33], v[0:1] op_sel_hi:[1,0]
	v_cvt_pk_bf16_f32 v2, v2, v3
	v_cvt_pk_bf16_f32 v3, v4, v5
	global_store_dwordx2 v[38:39], v[2:3], off offset:32
	v_pk_mul_f32 v[8:9], v[28:29], v[0:1] op_sel_hi:[1,0]
	s_nop 1
	v_mov_b32_e32 v2, v230
	v_mov_b32_e32 v3, v231
	v_mov_b32_e32 v4, v232
	v_mov_b32_e32 v5, v233
	v_pk_mul_f32 v[2:3], v[2:3], v[6:7]
	v_pk_mul_f32 v[4:5], v[4:5], v[8:9]
	v_cvt_pk_bf16_f32 v2, v2, v3
	v_cvt_pk_bf16_f32 v3, v4, v5
	global_store_dwordx2 v[38:39], v[2:3], off offset:64
	v_pk_mul_f32 v[6:7], v[24:25], v[0:1] op_sel_hi:[1,0]
	v_pk_mul_f32 v[8:9], v[20:21], v[0:1] op_sel_hi:[1,0]
	s_nop 1
	v_mov_b32_e32 v2, v234
	v_mov_b32_e32 v3, v235
	v_mov_b32_e32 v4, v236
	v_mov_b32_e32 v5, v237
	v_pk_mul_f32 v[2:3], v[2:3], v[6:7]
	v_pk_mul_f32 v[4:5], v[4:5], v[8:9]
	v_cvt_pk_bf16_f32 v2, v2, v3
	v_cvt_pk_bf16_f32 v3, v4, v5
	global_store_dwordx2 v[38:39], v[2:3], off offset:96
	v_pk_mul_f32 v[6:7], v[36:37], v[0:1] op_sel_hi:[1,0]
	v_pk_mul_f32 v[8:9], v[34:35], v[0:1] op_sel_hi:[1,0]
	s_nop 1
	v_mov_b32_e32 v2, v238
	v_mov_b32_e32 v3, v239
	v_mov_b32_e32 v4, v240
	v_mov_b32_e32 v5, v241
	v_pk_mul_f32 v[2:3], v[2:3], v[6:7]
	v_pk_mul_f32 v[4:5], v[4:5], v[8:9]
	v_cvt_pk_bf16_f32 v2, v2, v3
	v_cvt_pk_bf16_f32 v3, v4, v5
	global_store_dwordx2 v[38:39], v[2:3], off offset:128
	v_pk_mul_f32 v[6:7], v[22:23], v[0:1] op_sel_hi:[1,0]
	v_pk_mul_f32 v[8:9], v[18:19], v[0:1] op_sel_hi:[1,0]
	s_nop 1
	v_mov_b32_e32 v2, v242
	v_mov_b32_e32 v3, v243
	v_mov_b32_e32 v4, v244
	v_mov_b32_e32 v5, v245
	v_pk_mul_f32 v[2:3], v[2:3], v[6:7]
	v_pk_mul_f32 v[4:5], v[4:5], v[8:9]
	v_cvt_pk_bf16_f32 v2, v2, v3
	v_cvt_pk_bf16_f32 v3, v4, v5
	global_store_dwordx2 v[38:39], v[2:3], off offset:160
	v_pk_mul_f32 v[6:7], v[30:31], v[0:1] op_sel_hi:[1,0]
	v_pk_mul_f32 v[8:9], v[26:27], v[0:1] op_sel_hi:[1,0]
	s_nop 1
	v_mov_b32_e32 v2, v246
	v_mov_b32_e32 v3, v247
	v_mov_b32_e32 v4, v248
	v_mov_b32_e32 v5, v249
	v_pk_mul_f32 v[2:3], v[2:3], v[6:7]
	v_pk_mul_f32 v[4:5], v[4:5], v[8:9]
	v_cvt_pk_bf16_f32 v2, v2, v3
	v_cvt_pk_bf16_f32 v3, v4, v5
	global_store_dwordx2 v[38:39], v[2:3], off offset:192
	v_pk_mul_f32 v[6:7], v[14:15], v[0:1] op_sel_hi:[1,0]
	v_pk_mul_f32 v[8:9], v[10:11], v[0:1] op_sel_hi:[1,0]
	s_nop 1
	v_mov_b32_e32 v2, v172
	v_mov_b32_e32 v3, v173
	v_mov_b32_e32 v4, v174
	v_mov_b32_e32 v5, v175
	v_pk_mul_f32 v[2:3], v[6:7], v[2:3]
	v_pk_mul_f32 v[4:5], v[8:9], v[4:5]
	v_cvt_pk_bf16_f32 v2, v2, v3
	v_cvt_pk_bf16_f32 v3, v4, v5
	global_store_dwordx2 v[38:39], v[2:3], off offset:224
	s_mov_b32 s6, s100
	s_waitcnt lgkmcnt(0)
	s_add_i32 s40, s40, s6
	s_cmpk_gt_i32 s40, 0x7ff
	s_cbranch_scc1 .LBB0_194
